# leftover lgkmcnt(0) wait removal extended from the GEMM epilogues to the whole layer loop (129 waits), on top of the up-epilogue LDS-DMA prefetch
# speedup vs baseline: 1.0074x; 1.0004x over previous
; __device__ __forceinline__ float swap32_add(float v) { auto rr = __builtin_amdgcn_permlane32_swap(__float_as_uint(v), __float_as_uint(v), false, false); return __uint_as_float(rr[0]) + __uint_as_float(rr[1]); }
; template <int D, int DV, bool TAB, bool BITS, int KT> ...
;     ...
;     const float lt = swap32_add(l_run);
;     if (hi == 0) wsf[r32] = 1.0f / fmaxf(lt, 1e-30f);
;     __builtin_amdgcn_fence(__ATOMIC_RELEASE, "wavefront"); __builtin_amdgcn_wave_barrier();
; #pragma unroll
;     for (int j = 0; j < 4; ++j) { const f32x4 a4 = *(const f32x4*)(wsf + 8 * j + 4 * hi);
; #pragma unroll
;         for (int dt = 0; dt < DV / 32; ++dt) { o[dt][4 * j + 0] *= a4[0]; o[dt][4 * j + 1] *= a4[1]; o[dt][4 * j + 2] *= a4[2]; o[dt][4 * j + 3] *= a4[3]; } }
;     __builtin_amdgcn_fence(__ATOMIC_RELEASE, "wavefront"); __builtin_amdgcn_wave_barrier();
; __device__ __forceinline__ void unitA(unsigned char* lds, const MixCtx& c, int b, int h, int qb, bool ltab) {
;     ...
;     { const float* st = c.stash + (size_t)blockIdx.x * 512 + tid_o; asm volatile("" : "+v"(st) :: "memory");
; #pragma unroll
;       for (int dt = 0; dt < 4; ++dt)
; #pragma unroll
;           for (int r = 0; r < 16; ++r) oa[dt][r] = st[(size_t)(dt * 16 + r) * c.nthr]; }
.LBB0_336:
	s_waitcnt lgkmcnt(0)
	v_mul_f32_e32 v92, v48, v80
	v_mul_f32_e32 v48, v44, v76
	v_mul_f32_e32 v44, v40, v72
	v_mul_f32_e32 v40, v36, v68
	v_mul_f32_e32 v36, v2, v66
	v_mov_b32_e32 v2, v228
	v_readlane_b32 s4, v254, 30
	v_mul_f32_e32 v96, v32, v80
	v_mul_f32_e32 v32, v30, v78
	v_mul_f32_e32 v30, v60, v76
	v_mul_f32_e32 v60, v55, v71
	v_mul_f32_e32 v55, v3, v67
	v_readlane_b32 s5, v254, 31
	v_ashrrev_i32_e32 v3, 31, v2
	v_mul_f32_e32 v91, v65, v81
	v_mul_f32_e32 v65, v28, v76
	v_mul_f32_e32 v28, v41, v73
	v_mul_f32_e32 v41, v37, v69
	v_mul_f32_e32 v37, v35, v67
	v_mul_f32_e32 v0, v34, v66
	v_lshl_add_u64 v[34:35], v[2:3], 2, s[4:5]
	v_mul_f32_e32 v94, v64, v80
	v_mul_f32_e32 v64, v59, v75
	v_mul_f32_e32 v59, v54, v70
	flat_load_dword v54, v[34:35]
	v_lshl_add_u64 v[34:35], s[66:67], 2, v[34:35]
	flat_load_dword v3, v[34:35]
	v_lshl_add_u64 v[34:35], v[34:35], 0, s[68:69]
	v_mul_f32_e32 v93, v33, v81
	v_mul_f32_e32 v33, v31, v79
	v_mul_f32_e32 v31, v61, v77
	v_mul_f32_e32 v61, v56, v72
	flat_load_dword v56, v[34:35]
	v_lshl_add_u64 v[34:35], v[34:35], 0, s[68:69]
	v_mul_f32_e32 v90, v49, v81
	s_waitcnt vmcnt(0)
	v_mul_f32_e32 v98, v46, v78
	v_mul_f32_e32 v49, v45, v77
	v_mul_f32_e32 v46, v42, v74
	v_mul_f32_e32 v42, v38, v70
	v_mul_f32_e32 v45, v25, v73
	v_mul_f32_e32 v25, v24, v72
	v_mul_f32_e32 v24, v23, v71
	v_mul_f32_e32 v23, v22, v70
	v_mul_f32_e32 v6, v6, v70
	flat_load_dword v70, v[34:35]
	v_lshl_add_u64 v[34:35], v[34:35], 0, s[68:69]
	v_mul_f32_e32 v97, v63, v79
	v_mul_f32_e32 v63, v58, v74
	flat_load_dword v58, v[34:35]
	v_lshl_add_u64 v[34:35], v[34:35], 0, s[68:69]
	v_mul_f32_e32 v22, v53, v69
	v_mul_f32_e32 v53, v21, v69
	v_mul_f32_e32 v5, v5, v69
	flat_load_dword v69, v[34:35]
	v_lshl_add_u64 v[34:35], v[34:35], 0, s[68:69]
	v_mul_f32_e32 v99, v62, v78
	v_mul_f32_e32 v14, v14, v78
	v_mul_f32_e32 v78, v29, v77
	v_mul_f32_e32 v29, v27, v75
	v_mul_f32_e32 v27, v57, v73
	v_mul_f32_e32 v57, v52, v68
	v_mul_f32_e32 v21, v20, v68
	v_mul_f32_e32 v4, v4, v68
	flat_load_dword v68, v[34:35]
	v_lshl_add_u64 v[34:35], v[34:35], 0, s[68:69]
	v_mul_f32_e32 v95, v47, v79
	v_mul_f32_e32 v47, v43, v75
	v_mul_f32_e32 v43, v39, v71
	v_mul_f32_e32 v39, v51, v67
	v_mul_f32_e32 v20, v19, v67
	flat_load_dword v67, v[34:35]
	v_lshl_add_u64 v[34:35], v[34:35], 0, s[68:69]
	flat_load_dword v62, v[34:35]
	v_lshl_add_u64 v[34:35], v[34:35], 0, s[68:69]
	v_mul_f32_e32 v38, v50, v66
	v_mul_f32_e32 v19, v18, v66
	flat_load_dword v66, v[34:35]
	v_lshl_add_u64 v[34:35], v[34:35], 0, s[68:69]
	flat_load_dword v52, v[34:35]
	v_lshl_add_u64 v[34:35], v[34:35], 0, s[68:69]
	flat_load_dword v51, v[34:35]
	v_lshl_add_u64 v[34:35], v[34:35], 0, s[68:69]
	v_mul_f32_e32 v9, v9, v73
	v_mul_f32_e32 v8, v8, v72
	v_lshl_add_u64 v[72:73], v[34:35], 0, s[68:69]
	flat_load_dword v50, v[34:35]
	v_mul_f32_e32 v7, v7, v71
	flat_load_dword v35, v[72:73]
	v_lshl_add_u64 v[72:73], v[72:73], 0, s[68:69]
	flat_load_dword v34, v[72:73]
	v_lshl_add_u64 v[72:73], v[72:73], 0, s[68:69]
	flat_load_dword v18, v[72:73]
	v_lshl_add_u64 v[72:73], v[72:73], 0, s[68:69]
	flat_load_dword v71, v[72:73]
	v_lshl_add_u64 v[72:73], v[72:73], 0, s[68:69]
	v_mul_f32_e32 v26, v26, v74
	v_mul_f32_e32 v10, v10, v74
	flat_load_dword v74, v[72:73]
	v_lshl_add_u64 v[72:73], v[72:73], 0, s[68:69]
	v_mul_f32_e32 v11, v11, v75
	flat_load_dword v75, v[72:73]
	v_lshl_add_u64 v[72:73], v[72:73], 0, s[68:69]
	v_mul_f32_e32 v12, v12, v76
	flat_load_dword v76, v[72:73]
	v_lshl_add_u64 v[72:73], v[72:73], 0, s[68:69]
	v_mul_f32_e32 v13, v13, v77
	flat_load_dword v77, v[72:73]
	v_lshl_add_u64 v[72:73], v[72:73], 0, s[68:69]
	v_mul_f32_e32 v15, v15, v79
	flat_load_dword v79, v[72:73]
	v_lshl_add_u64 v[72:73], v[72:73], 0, s[68:69]
	v_mul_f32_e32 v16, v16, v80
	flat_load_dword v80, v[72:73]
	v_lshl_add_u64 v[72:73], v[72:73], 0, s[68:69]
	v_mul_f32_e32 v17, v17, v81
	flat_load_dword v81, v[72:73]
	v_lshl_add_u64 v[72:73], v[72:73], 0, s[68:69]
	flat_load_dword v83, v[72:73]
	v_lshl_add_u64 v[72:73], v[72:73], 0, s[68:69]
	flat_load_dword v85, v[72:73]
	v_lshl_add_u64 v[72:73], v[72:73], 0, s[68:69]
	flat_load_dword v87, v[72:73]
	v_lshl_add_u64 v[72:73], v[72:73], 0, s[68:69]
	flat_load_dword v101, v[72:73]
	v_lshl_add_u64 v[72:73], v[72:73], 0, s[68:69]
	flat_load_dword v102, v[72:73]
	v_lshl_add_u64 v[72:73], v[72:73], 0, s[68:69]
	flat_load_dword v103, v[72:73]
	v_lshl_add_u64 v[72:73], v[72:73], 0, s[68:69]
	flat_load_dword v104, v[72:73]
	v_lshl_add_u64 v[72:73], v[72:73], 0, s[68:69]
	flat_load_dword v105, v[72:73]
	v_lshl_add_u64 v[72:73], v[72:73], 0, s[68:69]
	flat_load_dword v82, v[72:73]
	v_lshl_add_u64 v[72:73], v[72:73], 0, s[68:69]
	flat_load_dword v84, v[72:73]
	v_lshl_add_u64 v[72:73], v[72:73], 0, s[68:69]
	flat_load_dword v86, v[72:73]
	v_lshl_add_u64 v[72:73], v[72:73], 0, s[68:69]
	flat_load_dword v106, v[72:73]
	v_lshl_add_u64 v[72:73], v[72:73], 0, s[68:69]
	flat_load_dword v107, v[72:73]
	v_lshl_add_u64 v[72:73], v[72:73], 0, s[68:69]
	flat_load_dword v108, v[72:73]
	v_lshl_add_u64 v[72:73], v[72:73], 0, s[68:69]
	flat_load_dword v109, v[72:73]
	v_lshl_add_u64 v[72:73], v[72:73], 0, s[68:69]
	flat_load_dword v110, v[72:73]
	v_lshl_add_u64 v[72:73], v[72:73], 0, s[68:69]
	flat_load_dword v111, v[72:73]
	v_lshl_add_u64 v[72:73], v[72:73], 0, s[68:69]
	flat_load_dword v112, v[72:73]
	v_lshl_add_u64 v[72:73], v[72:73], 0, s[68:69]
	flat_load_dword v113, v[72:73]
	v_lshl_add_u64 v[72:73], v[72:73], 0, s[68:69]
	flat_load_dword v114, v[72:73]
	v_lshl_add_u64 v[72:73], v[72:73], 0, s[68:69]
	flat_load_dword v115, v[72:73]
	v_lshl_add_u64 v[72:73], v[72:73], 0, s[68:69]
	flat_load_dword v116, v[72:73]
; __device__ __forceinline__ void unitA(unsigned char* lds, const MixCtx& c, int b, int h, int qb, bool ltab) {
;     ...
;     float ss[16];
; #pragma unroll
;     for (int r = 0; r < 16; ++r) { float s = 0.f;
; #pragma unroll
;         for (int dt = 0; dt < 4; ++dt) { const float v = oa[dt][r] - lam * ob[dt][r]; oa[dt][r] = v; s += v * v; }
;         ss[r] = s; }
; #pragma unroll
;     for (int r = 0; r < 16; ++r) {
; #pragma unroll
;         for (int o = 1; o < 32; o <<= 1) ss[r] += __shfl_xor(ss[r], o);
;         ss[r] = (1.0f - lam_init) / sqrtf(ss[r] * (1.f / 128.f) + EPSN); }
	v_lshl_add_u64 v[72:73], v[72:73], 0, s[68:69]
	flat_load_dword v117, v[72:73]
	v_lshl_add_u64 v[72:73], v[72:73], 0, s[68:69]
	flat_load_dword v118, v[72:73]
	v_lshl_add_u64 v[72:73], v[72:73], 0, s[68:69]
	flat_load_dword v100, v[72:73]
	v_lshl_add_u64 v[72:73], v[72:73], 0, s[68:69]
	flat_load_dword v119, v[72:73]
	v_lshl_add_u64 v[72:73], v[72:73], 0, s[68:69]
	flat_load_dword v120, v[72:73]
	v_lshl_add_u64 v[72:73], v[72:73], 0, s[68:69]
	flat_load_dword v121, v[72:73]
	v_lshl_add_u64 v[72:73], v[72:73], 0, s[68:69]
	flat_load_dword v122, v[72:73]
	v_lshl_add_u64 v[72:73], v[72:73], 0, s[68:69]
	flat_load_dword v123, v[72:73]
	v_lshl_add_u64 v[72:73], v[72:73], 0, s[68:69]
	flat_load_dword v124, v[72:73]
	v_lshl_add_u64 v[72:73], v[72:73], 0, s[68:69]
	flat_load_dword v125, v[72:73]
	v_lshl_add_u64 v[72:73], v[72:73], 0, s[68:69]
	flat_load_dword v126, v[72:73]
	v_lshl_add_u64 v[72:73], v[72:73], 0, s[68:69]
	flat_load_dword v127, v[72:73]
	v_lshl_add_u64 v[72:73], v[72:73], 0, s[68:69]
	flat_load_dword v128, v[72:73]
	v_lshl_add_u64 v[72:73], v[72:73], 0, s[68:69]
	flat_load_dword v129, v[72:73]
	v_lshl_add_u64 v[72:73], v[72:73], 0, s[68:69]
	flat_load_dword v130, v[72:73]
	v_lshl_add_u64 v[72:73], v[72:73], 0, s[68:69]
	flat_load_dword v131, v[72:73]
	v_lshl_add_u64 v[72:73], v[72:73], 0, s[68:69]
	flat_load_dword v132, v[72:73]
	v_lshl_add_u64 v[72:73], v[72:73], 0, s[68:69]
	flat_load_dword v73, v[72:73]
	s_waitcnt lgkmcnt(0)
	v_fma_f32 v54, -v36, v89, v54
	s_waitcnt vmcnt(0)
	v_fma_f32 v36, -v19, v89, v71
	v_mul_f32_e32 v133, v36, v36
	v_fma_f32 v58, -v6, v89, v58
	v_fmac_f32_e32 v133, v54, v54
	v_fma_f32 v62, -v10, v89, v62
	s_lshl_b32 s0, s0, 7
	s_ashr_i32 s1, s0, 31
	v_readlane_b32 s4, v253, 2
	s_lshl_b64 s[0:1], s[0:1], 2
	v_readlane_b32 s6, v253, 4
	v_readlane_b32 s5, v253, 3
	v_readlane_b32 s7, v253, 5
	s_add_u32 s4, s6, s0
	v_fma_f32 v55, -v55, v89, v3
	v_fma_f32 v56, -v4, v89, v56
	s_addc_u32 s5, s7, s1
	v_fma_f32 v19, -v38, v89, v82
	v_fma_f32 v38, -v20, v89, v74
	v_fma_f32 v20, -v39, v89, v84
	v_fma_f32 v39, -v21, v89, v75
	v_fma_f32 v21, -v57, v89, v86
	v_fma_f32 v57, -v5, v89, v70
	v_fmac_f32_e32 v133, v19, v19
	v_fma_f32 v22, -v22, v89, v106
	v_and_b32_e32 v2, 31, v2
	v_readlane_b32 s16, v253, 14
	v_readlane_b32 s17, v253, 15
	v_readlane_b32 s18, v253, 16
	v_readlane_b32 s19, v253, 17
	s_mov_b64 s[16:17], s[24:25]
	v_fma_f32 v27, -v27, v89, v110
	s_mov_b64 s[18:19], s[50:51]
	v_readlane_b32 s8, v253, 6
	v_readlane_b32 s9, v253, 7
	v_readlane_b32 s10, v253, 8
	v_readlane_b32 s11, v253, 9
	v_fma_f32 v30, -v30, v89, v113
	v_readlane_b32 s12, v253, 10
	v_fma_f32 v31, -v31, v89, v114
	v_readlane_b32 s13, v253, 11
	v_readlane_b32 s14, v253, 12
	v_readlane_b32 s15, v253, 13
	v_fma_f32 v0, -v0, v89, v100
	v_fmac_f32_e32 v133, v0, v0
	v_fma_f32 v3, -v37, v89, v119
	v_mul_f32_e32 v100, v38, v38
	v_fma_f32 v4, -v40, v89, v120
	v_fma_f32 v40, -v53, v89, v76
	v_fma_f32 v5, -v41, v89, v121
	v_fma_f32 v41, -v23, v89, v77
	v_fma_f32 v23, -v59, v89, v107
	v_fma_f32 v59, -v7, v89, v69
	v_fma_f32 v69, -v17, v89, v18
	v_and_b32_e32 v18, 64, v229
	v_fma_f32 v6, -v42, v89, v122
	v_fma_f32 v42, -v24, v89, v79
	v_fma_f32 v24, -v60, v89, v108
	v_fma_f32 v60, -v8, v89, v68
	v_fma_f32 v8, -v44, v89, v124
	v_fma_f32 v44, -v45, v89, v81
	v_fma_f32 v45, -v26, v89, v83
	v_add_u32_e32 v18, 64, v18
	v_xor_b32_e32 v26, 1, v229
	v_cmp_lt_i32_e32 vcc, v26, v18
	v_xor_b32_e32 v77, 2, v229
	v_fma_f32 v10, -v46, v89, v126
	v_cndmask_b32_e32 v26, v229, v26, vcc
	v_lshlrev_b32_e32 v75, 2, v26
	v_cmp_lt_i32_e32 vcc, v77, v18
	v_fma_f32 v46, -v29, v89, v85
	v_fma_f32 v29, -v64, v89, v112
	v_cndmask_b32_e32 v77, v229, v77, vcc
	s_nop 1
	v_add_f32_dpp v26, v133, v133 quad_perm:[1,0,3,2] row_mask:0xf bank_mask:0xf
	v_lshlrev_b32_e32 v77, 2, v77
	v_fma_f32 v64, -v12, v89, v52
	v_fma_f32 v12, -v48, v89, v128
	v_fma_f32 v48, -v78, v89, v101
	v_fma_f32 v7, -v43, v89, v123
	v_fma_f32 v43, -v25, v89, v80
	v_fma_f32 v17, -v90, v89, v73
	v_sub_f32_e32 v73, 1.0, v88
	s_nop 1
	v_add_f32_dpp v26, v26, v26 quad_perm:[2,3,0,1] row_mask:0xf bank_mask:0xf
	v_xor_b32_e32 v78, 4, v229
	v_cmp_lt_i32_e32 vcc, v78, v18
	v_fma_f32 v25, -v61, v89, v109
	v_fma_f32 v61, -v9, v89, v67
	v_cndmask_b32_e32 v78, v229, v78, vcc
	v_lshlrev_b32_e32 v78, 2, v78
	v_fma_f32 v9, -v28, v89, v125
	v_fma_f32 v28, -v63, v89, v111
	v_fma_f32 v63, -v11, v89, v66
	v_fma_f32 v11, -v47, v89, v127
	s_nop 1
	v_add_f32_dpp v26, v26, v26 row_half_mirror row_mask:0xf bank_mask:0xf
	v_xor_b32_e32 v79, 8, v229
	v_cmp_lt_i32_e32 vcc, v79, v18
	v_fma_f32 v47, -v65, v89, v87
	v_fma_f32 v65, -v13, v89, v51
	v_cndmask_b32_e32 v79, v229, v79, vcc
	v_lshlrev_b32_e32 v79, 2, v79
	v_fma_f32 v13, -v49, v89, v129
	v_fma_f32 v66, -v14, v89, v50
	v_fma_f32 v49, -v32, v89, v102
	v_fma_f32 v32, -v99, v89, v115
	s_nop 1
	v_add_f32_dpp v26, v26, v26 row_mirror row_mask:0xf bank_mask:0xf
	v_xor_b32_e32 v80, 16, v229
	v_cmp_lt_i32_e32 vcc, v80, v18
	v_fma_f32 v14, -v98, v89, v130
	v_fma_f32 v67, -v15, v89, v35
	v_cndmask_b32_e32 v18, v229, v80, vcc
	v_lshlrev_b32_e32 v80, 2, v18
	v_mov_b32_e32 v18, v26
	s_nop 1
	v_permlane16_swap_b32_e32 v18, v26
	v_fma_f32 v50, -v33, v89, v103
	v_fma_f32 v33, -v97, v89, v116
	v_fma_f32 v15, -v95, v89, v131
	v_fma_f32 v68, -v16, v89, v34
	v_add_f32_e32 v18, v26, v18
	v_fmamk_f32 v18, v18, 0x3c000000, v230
	v_fma_f32 v51, -v96, v89, v104
	v_fma_f32 v34, -v94, v89, v117
	v_fma_f32 v16, -v92, v89, v132
	v_fma_f32 v52, -v93, v89, v105
	v_fma_f32 v35, -v91, v89, v118
	v_fmac_f32_e32 v100, v55, v55
	v_fmac_f32_e32 v100, v20, v20
	v_fmac_f32_e32 v100, v3, v3
	v_mul_f32_e32 v37, v39, v39
; __device__ __forceinline__ void unitA(unsigned char* lds, const MixCtx& c, int b, int h, int qb, bool ltab) {
;     ...
;     float ss[16];
; #pragma unroll
;     for (int r = 0; r < 16; ++r) { float s = 0.f;
; #pragma unroll
;         for (int dt = 0; dt < 4; ++dt) { const float v = oa[dt][r] - lam * ob[dt][r]; oa[dt][r] = v; s += v * v; }
;         ss[r] = s; }
; #pragma unroll
;     for (int r = 0; r < 16; ++r) {
; #pragma unroll
;         for (int o = 1; o < 32; o <<= 1) ss[r] += __shfl_xor(ss[r], o);
;         ss[r] = (1.0f - lam_init) / sqrtf(ss[r] * (1.f / 128.f) + EPSN); }
	v_fmac_f32_e32 v37, v56, v56
	v_fmac_f32_e32 v37, v21, v21
	v_fmac_f32_e32 v37, v4, v4
	v_mul_f32_e32 v53, v40, v40
	v_rsq_f32_e32 v18, v18
	s_nop 0
	v_mul_f32_e32 v18, v73, v18
	v_fmac_f32_e32 v53, v57, v57
	v_fmac_f32_e32 v53, v22, v22
	v_fmac_f32_e32 v53, v5, v5
	v_mul_f32_e32 v70, v41, v41
	s_nop 1
	v_add_f32_dpp v26, v100, v100 quad_perm:[1,0,3,2] row_mask:0xf bank_mask:0xf
	v_fmac_f32_e32 v70, v58, v58
	v_fmac_f32_e32 v70, v23, v23
	v_fmac_f32_e32 v70, v6, v6
	v_mul_f32_e32 v71, v42, v42
	s_nop 1
	v_add_f32_dpp v26, v26, v26 quad_perm:[2,3,0,1] row_mask:0xf bank_mask:0xf
	v_fmac_f32_e32 v71, v59, v59
	v_fmac_f32_e32 v71, v24, v24
	v_fmac_f32_e32 v71, v7, v7
	v_mul_f32_e32 v76, v43, v43
	s_nop 1
	v_add_f32_dpp v26, v26, v26 row_half_mirror row_mask:0xf bank_mask:0xf
	v_fmac_f32_e32 v76, v60, v60
	v_fmac_f32_e32 v76, v25, v25
	v_fmac_f32_e32 v76, v8, v8
	v_mul_f32_e32 v82, v44, v44
	s_nop 1
	v_add_f32_dpp v26, v26, v26 row_mirror row_mask:0xf bank_mask:0xf
	v_mov_b32_e32 v88, v26
	s_nop 1
	v_permlane16_swap_b32_e32 v88, v26
	v_fmac_f32_e32 v82, v61, v61
	v_fmac_f32_e32 v82, v27, v27
	v_fmac_f32_e32 v82, v9, v9
	v_mul_f32_e32 v84, v45, v45
	v_add_f32_e32 v26, v26, v88
	v_fmamk_f32 v26, v26, 0x3c000000, v230
	v_fmac_f32_e32 v84, v62, v62
	v_fmac_f32_e32 v84, v28, v28
	v_fmac_f32_e32 v84, v10, v10
	v_mul_f32_e32 v86, v46, v46
	v_fmac_f32_e32 v86, v63, v63
	v_fmac_f32_e32 v86, v29, v29
	v_fmac_f32_e32 v86, v11, v11
	v_mul_f32_e32 v87, v47, v47
	v_fmac_f32_e32 v87, v64, v64
	v_fmac_f32_e32 v87, v30, v30
	v_fmac_f32_e32 v87, v12, v12
	v_mul_f32_e32 v85, v48, v48
	v_rsq_f32_e32 v26, v26
	s_nop 0
	v_mul_f32_e32 v26, v73, v26
	v_fmac_f32_e32 v85, v65, v65
	v_fmac_f32_e32 v85, v31, v31
	v_fmac_f32_e32 v85, v13, v13
	v_mul_f32_e32 v83, v49, v49
	s_nop 1
	v_add_f32_dpp v37, v37, v37 quad_perm:[1,0,3,2] row_mask:0xf bank_mask:0xf
	v_fmac_f32_e32 v83, v66, v66
	v_fmac_f32_e32 v83, v32, v32
	v_fmac_f32_e32 v83, v14, v14
	v_mul_f32_e32 v81, v50, v50
	s_nop 1
	v_add_f32_dpp v37, v37, v37 quad_perm:[2,3,0,1] row_mask:0xf bank_mask:0xf
	v_fmac_f32_e32 v81, v67, v67
	v_fmac_f32_e32 v81, v33, v33
	v_fmac_f32_e32 v81, v15, v15
	v_mul_f32_e32 v74, v51, v51
	s_nop 1
	v_add_f32_dpp v37, v37, v37 row_half_mirror row_mask:0xf bank_mask:0xf
	v_fmac_f32_e32 v74, v68, v68
	v_fmac_f32_e32 v74, v34, v34
	v_fmac_f32_e32 v74, v16, v16
	v_mul_f32_e32 v72, v52, v52
	s_nop 1
	v_add_f32_dpp v37, v37, v37 row_mirror row_mask:0xf bank_mask:0xf
	v_mov_b32_e32 v88, v37
	s_nop 1
	v_permlane16_swap_b32_e32 v88, v37
	v_fmac_f32_e32 v72, v69, v69
	v_fmac_f32_e32 v72, v35, v35
	v_fmac_f32_e32 v72, v17, v17
	v_mul_f32_e32 v54, v54, v18
	v_add_f32_e32 v37, v37, v88
	v_fmamk_f32 v37, v37, 0x3c000000, v230
	v_mul_f32_e32 v36, v36, v18
	v_mul_f32_e32 v38, v38, v26
	v_mul_f32_e32 v19, v19, v18
	v_mul_f32_e32 v20, v20, v26
	v_mul_f32_e32 v0, v0, v18
	v_rsq_f32_e32 v37, v37
	s_nop 0
	v_mul_f32_e32 v37, v73, v37
	v_mul_f32_e32 v39, v39, v37
	v_mul_f32_e32 v21, v21, v37
	s_nop 1
	v_add_f32_dpp v53, v53, v53 quad_perm:[1,0,3,2] row_mask:0xf bank_mask:0xf
	s_nop 1
	v_add_f32_dpp v53, v53, v53 quad_perm:[2,3,0,1] row_mask:0xf bank_mask:0xf
	s_nop 1
	v_add_f32_dpp v53, v53, v53 row_half_mirror row_mask:0xf bank_mask:0xf
	s_nop 1
	v_add_f32_dpp v53, v53, v53 row_mirror row_mask:0xf bank_mask:0xf
	v_mov_b32_e32 v88, v53
	s_nop 1
	v_permlane16_swap_b32_e32 v88, v53
	v_add_f32_e32 v53, v53, v88
	v_fmamk_f32 v53, v53, 0x3c000000, v230
	v_rsq_f32_e32 v53, v53
	s_nop 0
	v_mul_f32_e32 v53, v73, v53
	v_mul_f32_e32 v40, v40, v53
	v_mul_f32_e32 v22, v22, v53
	s_nop 1
	v_add_f32_dpp v70, v70, v70 quad_perm:[1,0,3,2] row_mask:0xf bank_mask:0xf
	s_nop 1
	v_add_f32_dpp v70, v70, v70 quad_perm:[2,3,0,1] row_mask:0xf bank_mask:0xf
	s_nop 1
	v_add_f32_dpp v70, v70, v70 row_half_mirror row_mask:0xf bank_mask:0xf
	s_nop 1
	v_add_f32_dpp v70, v70, v70 row_mirror row_mask:0xf bank_mask:0xf
	v_mov_b32_e32 v88, v70
	s_nop 1
	v_permlane16_swap_b32_e32 v88, v70
	v_add_f32_e32 v70, v70, v88
	v_fmamk_f32 v70, v70, 0x3c000000, v230
	v_rsq_f32_e32 v70, v70
	s_nop 0
	v_mul_f32_e32 v70, v73, v70
	v_mul_f32_e32 v41, v41, v70
	v_mul_f32_e32 v23, v23, v70
	s_nop 1
	v_add_f32_dpp v71, v71, v71 quad_perm:[1,0,3,2] row_mask:0xf bank_mask:0xf
	s_nop 1
	v_add_f32_dpp v71, v71, v71 quad_perm:[2,3,0,1] row_mask:0xf bank_mask:0xf
	s_nop 1
	v_add_f32_dpp v71, v71, v71 row_half_mirror row_mask:0xf bank_mask:0xf
	s_nop 1
	v_add_f32_dpp v71, v71, v71 row_mirror row_mask:0xf bank_mask:0xf
	v_mov_b32_e32 v88, v71
	s_nop 1
	v_permlane16_swap_b32_e32 v88, v71
	v_add_f32_e32 v71, v71, v88
	v_fmamk_f32 v71, v71, 0x3c000000, v230
	v_rsq_f32_e32 v71, v71
	s_nop 0
	v_mul_f32_e32 v71, v73, v71
	v_mul_f32_e32 v42, v42, v71
	v_mul_f32_e32 v24, v24, v71
	s_nop 1
	v_add_f32_dpp v76, v76, v76 quad_perm:[1,0,3,2] row_mask:0xf bank_mask:0xf
	s_nop 1
	v_add_f32_dpp v76, v76, v76 quad_perm:[2,3,0,1] row_mask:0xf bank_mask:0xf
	s_nop 1
	v_add_f32_dpp v76, v76, v76 row_half_mirror row_mask:0xf bank_mask:0xf
	s_nop 1
	v_add_f32_dpp v76, v76, v76 row_mirror row_mask:0xf bank_mask:0xf
	v_mov_b32_e32 v88, v76
	s_nop 1
	v_permlane16_swap_b32_e32 v88, v76
	v_add_f32_e32 v76, v76, v88
	v_fmamk_f32 v76, v76, 0x3c000000, v230
	v_rsq_f32_e32 v76, v76
	s_nop 0
	v_mul_f32_e32 v76, v73, v76
	v_mul_f32_e32 v43, v43, v76
	v_mul_f32_e32 v25, v25, v76
	s_nop 1
	v_add_f32_dpp v82, v82, v82 quad_perm:[1,0,3,2] row_mask:0xf bank_mask:0xf
	s_nop 1
	v_add_f32_dpp v82, v82, v82 quad_perm:[2,3,0,1] row_mask:0xf bank_mask:0xf
	s_nop 1
	v_add_f32_dpp v82, v82, v82 row_half_mirror row_mask:0xf bank_mask:0xf
	s_nop 1
	v_add_f32_dpp v82, v82, v82 row_mirror row_mask:0xf bank_mask:0xf
; __device__ __forceinline__ void unitA(unsigned char* lds, const MixCtx& c, int b, int h, int qb, bool ltab) {
;     ...
;     for (int r = 0; r < 16; ++r) {
; #pragma unroll
;         for (int o = 1; o < 32; o <<= 1) ss[r] += __shfl_xor(ss[r], o);
;         ss[r] = (1.0f - lam_init) / sqrtf(ss[r] * (1.f / 128.f) + EPSN); }
; #pragma unroll
;     for (int dt = 0; dt < 4; ++dt) { const float g = subln[dt * 32 + r32];
; #pragma unroll
;         for (int r = 0; r < 16; ++r) oa[dt][r] = oa[dt][r] * ss[r] * g; }
	v_mov_b32_e32 v88, v82
	s_nop 1
	v_permlane16_swap_b32_e32 v88, v82
	v_add_f32_e32 v82, v82, v88
	v_fmamk_f32 v82, v82, 0x3c000000, v230
	v_rsq_f32_e32 v82, v82
	s_nop 0
	v_mul_f32_e32 v82, v73, v82
	v_mul_f32_e32 v44, v44, v82
	v_mul_f32_e32 v27, v27, v82
	s_nop 1
	v_add_f32_dpp v84, v84, v84 quad_perm:[1,0,3,2] row_mask:0xf bank_mask:0xf
	s_nop 1
	v_add_f32_dpp v84, v84, v84 quad_perm:[2,3,0,1] row_mask:0xf bank_mask:0xf
	s_nop 1
	v_add_f32_dpp v84, v84, v84 row_half_mirror row_mask:0xf bank_mask:0xf
	s_nop 1
	v_add_f32_dpp v84, v84, v84 row_mirror row_mask:0xf bank_mask:0xf
	v_mov_b32_e32 v88, v84
	s_nop 1
	v_permlane16_swap_b32_e32 v88, v84
	v_add_f32_e32 v84, v84, v88
	v_fmamk_f32 v84, v84, 0x3c000000, v230
	v_rsq_f32_e32 v84, v84
	s_nop 0
	v_mul_f32_e32 v84, v73, v84
	v_mul_f32_e32 v45, v45, v84
	v_mul_f32_e32 v28, v28, v84
	s_nop 1
	v_add_f32_dpp v86, v86, v86 quad_perm:[1,0,3,2] row_mask:0xf bank_mask:0xf
	s_nop 1
	v_add_f32_dpp v86, v86, v86 quad_perm:[2,3,0,1] row_mask:0xf bank_mask:0xf
	s_nop 1
	v_add_f32_dpp v86, v86, v86 row_half_mirror row_mask:0xf bank_mask:0xf
	s_nop 1
	v_add_f32_dpp v86, v86, v86 row_mirror row_mask:0xf bank_mask:0xf
	v_mov_b32_e32 v88, v86
	s_nop 1
	v_permlane16_swap_b32_e32 v88, v86
	v_add_f32_e32 v86, v86, v88
	v_fmamk_f32 v86, v86, 0x3c000000, v230
	v_rsq_f32_e32 v86, v86
	s_nop 0
	v_mul_f32_e32 v86, v73, v86
	v_mul_f32_e32 v46, v46, v86
	v_mul_f32_e32 v29, v29, v86
	s_nop 1
	v_add_f32_dpp v87, v87, v87 quad_perm:[1,0,3,2] row_mask:0xf bank_mask:0xf
	s_nop 1
	v_add_f32_dpp v87, v87, v87 quad_perm:[2,3,0,1] row_mask:0xf bank_mask:0xf
	s_nop 1
	v_add_f32_dpp v87, v87, v87 row_half_mirror row_mask:0xf bank_mask:0xf
	s_nop 1
	v_add_f32_dpp v87, v87, v87 row_mirror row_mask:0xf bank_mask:0xf
	v_mov_b32_e32 v88, v87
	s_nop 1
	v_permlane16_swap_b32_e32 v88, v87
	v_add_f32_e32 v87, v87, v88
	v_fmamk_f32 v87, v87, 0x3c000000, v230
	v_rsq_f32_e32 v87, v87
	s_nop 0
	v_mul_f32_e32 v87, v73, v87
	v_mul_f32_e32 v47, v47, v87
	v_mul_f32_e32 v30, v30, v87
	s_nop 1
	v_add_f32_dpp v85, v85, v85 quad_perm:[1,0,3,2] row_mask:0xf bank_mask:0xf
	s_nop 1
	v_add_f32_dpp v85, v85, v85 quad_perm:[2,3,0,1] row_mask:0xf bank_mask:0xf
	s_nop 1
	v_add_f32_dpp v85, v85, v85 row_half_mirror row_mask:0xf bank_mask:0xf
	s_nop 1
	v_add_f32_dpp v85, v85, v85 row_mirror row_mask:0xf bank_mask:0xf
	v_mov_b32_e32 v88, v85
	s_nop 1
	v_permlane16_swap_b32_e32 v88, v85
	v_add_f32_e32 v85, v85, v88
	v_fmamk_f32 v85, v85, 0x3c000000, v230
	v_rsq_f32_e32 v85, v85
	s_nop 0
	v_mul_f32_e32 v85, v73, v85
	v_mul_f32_e32 v48, v48, v85
	v_mul_f32_e32 v31, v31, v85
	s_nop 1
	v_add_f32_dpp v83, v83, v83 quad_perm:[1,0,3,2] row_mask:0xf bank_mask:0xf
	s_nop 1
	v_add_f32_dpp v83, v83, v83 quad_perm:[2,3,0,1] row_mask:0xf bank_mask:0xf
	s_nop 1
	v_add_f32_dpp v83, v83, v83 row_half_mirror row_mask:0xf bank_mask:0xf
	s_nop 1
	v_add_f32_dpp v83, v83, v83 row_mirror row_mask:0xf bank_mask:0xf
	v_mov_b32_e32 v88, v83
	s_nop 1
	v_permlane16_swap_b32_e32 v88, v83
	v_add_f32_e32 v83, v83, v88
	v_fmamk_f32 v83, v83, 0x3c000000, v230
	v_rsq_f32_e32 v83, v83
	s_nop 0
	v_mul_f32_e32 v83, v73, v83
	v_mul_f32_e32 v49, v49, v83
	v_mul_f32_e32 v32, v32, v83
	s_nop 1
	v_add_f32_dpp v81, v81, v81 quad_perm:[1,0,3,2] row_mask:0xf bank_mask:0xf
	s_nop 1
	v_add_f32_dpp v81, v81, v81 quad_perm:[2,3,0,1] row_mask:0xf bank_mask:0xf
	s_nop 1
	v_add_f32_dpp v81, v81, v81 row_half_mirror row_mask:0xf bank_mask:0xf
	s_nop 1
	v_add_f32_dpp v81, v81, v81 row_mirror row_mask:0xf bank_mask:0xf
	v_mov_b32_e32 v88, v81
	s_nop 1
	v_permlane16_swap_b32_e32 v88, v81
	v_add_f32_e32 v81, v81, v88
	v_fmamk_f32 v81, v81, 0x3c000000, v230
	v_rsq_f32_e32 v81, v81
	s_nop 0
	v_mul_f32_e32 v81, v73, v81
	v_mul_f32_e32 v50, v50, v81
	v_mul_f32_e32 v33, v33, v81
	s_nop 1
	v_add_f32_dpp v74, v74, v74 quad_perm:[1,0,3,2] row_mask:0xf bank_mask:0xf
	s_nop 1
	v_add_f32_dpp v72, v72, v72 quad_perm:[1,0,3,2] row_mask:0xf bank_mask:0xf
	s_nop 1
	v_add_f32_dpp v74, v74, v74 quad_perm:[2,3,0,1] row_mask:0xf bank_mask:0xf
	s_nop 1
	v_add_f32_dpp v72, v72, v72 quad_perm:[2,3,0,1] row_mask:0xf bank_mask:0xf
	s_nop 1
	v_add_f32_dpp v74, v74, v74 row_half_mirror row_mask:0xf bank_mask:0xf
	s_nop 1
	v_add_f32_dpp v72, v72, v72 row_half_mirror row_mask:0xf bank_mask:0xf
	s_nop 1
	v_add_f32_dpp v74, v74, v74 row_mirror row_mask:0xf bank_mask:0xf
	v_mov_b32_e32 v88, v74
	s_nop 1
	v_permlane16_swap_b32_e32 v88, v74
	s_nop 1
	v_add_f32_dpp v72, v72, v72 row_mirror row_mask:0xf bank_mask:0xf
	v_mov_b32_e32 v75, v72
	s_nop 1
	v_permlane16_swap_b32_e32 v75, v72
	v_add_f32_e32 v74, v74, v88
	v_fmamk_f32 v74, v74, 0x3c000000, v230
	s_waitcnt lgkmcnt(0)
	v_add_f32_e32 v72, v72, v75
	v_fmamk_f32 v72, v72, 0x3c000000, v230
	v_lshlrev_b32_e32 v89, 2, v2
	global_load_dword v2, v89, s[4:5]
	v_rsq_f32_e32 v74, v74
	s_nop 0
	v_mul_f32_e32 v74, v73, v74
	v_mul_f32_e32 v51, v51, v74
	v_mul_f32_e32 v34, v34, v74
	s_waitcnt vmcnt(0)
	v_mul_f32_e32 v88, v54, v2
	v_mul_f32_e32 v54, v55, v26
	s_lshl_b64 s[0:1], s[54:55], 11
	s_add_u32 s0, s2, s0
	s_addc_u32 s1, s3, s1
	v_mul_f32_e32 v80, v54, v2
	v_mul_f32_e32 v54, v56, v37
	v_mul_f32_e32 v79, v54, v2
	v_mul_f32_e32 v54, v57, v53
	v_mul_f32_e32 v78, v54, v2
	v_mul_f32_e32 v54, v58, v70
	v_mul_f32_e32 v77, v54, v2
	v_mul_f32_e32 v54, v59, v71
	v_rsq_f32_e32 v72, v72
	s_nop 0
	v_mul_f32_e32 v72, v73, v72
	v_mul_f32_e32 v75, v54, v2
	v_mul_f32_e32 v54, v60, v76
	v_mul_f32_e32 v73, v54, v2
	v_mul_f32_e32 v54, v61, v82
	v_mul_f32_e32 v61, v54, v2
	v_mul_f32_e32 v54, v62, v84
	v_mul_f32_e32 v60, v54, v2
	v_mul_f32_e32 v54, v63, v86
	v_mul_f32_e32 v59, v54, v2
	v_mul_f32_e32 v54, v64, v87
	v_mul_f32_e32 v58, v54, v2
	v_mul_f32_e32 v54, v65, v85
	v_mul_f32_e32 v57, v54, v2
	v_mul_f32_e32 v54, v66, v83
	v_mul_f32_e32 v56, v54, v2
	v_mul_f32_e32 v54, v67, v81
	v_mul_f32_e32 v55, v54, v2
	v_mul_f32_e32 v54, v68, v74
	v_mul_f32_e32 v62, v69, v72
	v_mul_f32_e32 v54, v2, v54
	v_mul_f32_e32 v2, v2, v62
	global_load_dword v62, v89, s[4:5] offset:128
	v_mul_f32_e32 v52, v52, v72
	v_mul_f32_e32 v35, v35, v72
	s_waitcnt vmcnt(0)
; __device__ __forceinline__ unsigned cvtpk(float lo, float hi) { f32x2_t v = {lo, hi}; bf16x2_t b = __builtin_convertvector(v, bf16x2_t); return __builtin_bit_cast(unsigned, b); }
; __device__ __forceinline__ int crowc(int r) { return (r & 3) + 8 * (r >> 2); }
; template <int DV>
; __device__ __forceinline__ void attn_store(const f32x16 (&o)[DV / 32], bf16_t* Op, int ldo) {
;     int tid_o = threadIdx.x; asm volatile("" : "+v"(tid_o));
;     const int lane = tid_o & 63, wid = tid_o >> 6, r32 = lane & 31, hi = lane >> 5;
; #pragma unroll
;     for (int dt = 0; dt < DV / 32; ++dt)
; #pragma unroll
;         for (int r = 0; r < 16; ++r) { const int row = 32 * wid + crowc(r) + 4 * hi; Op[(size_t)row * ldo + dt * 32 + r32] = (bf16_t)(cvtpk(o[dt][r], 0.f) & 0xffffu); }
; __device__ __forceinline__ void unitA(unsigned char* lds, const MixCtx& c, int b, int h, int qb, bool ltab) {
;     ...
;     for (int dt = 0; dt < 4; ++dt) { const float g = subln[dt * 32 + r32];
; #pragma unroll
;         for (int r = 0; r < 16; ++r) oa[dt][r] = oa[dt][r] * ss[r] * g; }
;     attn_store<128>(oa, c.MIX + (tokb + q0) * DM + h * 128, DM);
	v_mul_f32_e32 v36, v36, v62
	v_mul_f32_e32 v38, v38, v62
	v_mul_f32_e32 v39, v39, v62
	v_mul_f32_e32 v40, v40, v62
	v_mul_f32_e32 v41, v41, v62
	v_mul_f32_e32 v42, v42, v62
	v_mul_f32_e32 v43, v43, v62
	v_mul_f32_e32 v44, v44, v62
	v_mul_f32_e32 v45, v45, v62
	v_mul_f32_e32 v46, v46, v62
	v_mul_f32_e32 v47, v47, v62
	v_mul_f32_e32 v48, v48, v62
	v_mul_f32_e32 v49, v49, v62
	v_mul_f32_e32 v50, v50, v62
	v_mul_f32_e32 v51, v62, v51
	v_mul_f32_e32 v52, v62, v52
	global_load_dword v62, v89, s[4:5] offset:256
	s_waitcnt vmcnt(0)
	v_mul_f32_e32 v19, v19, v62
	v_mul_f32_e32 v20, v20, v62
	v_mul_f32_e32 v21, v21, v62
	v_mul_f32_e32 v22, v22, v62
	v_mul_f32_e32 v23, v23, v62
	v_mul_f32_e32 v24, v24, v62
	v_mul_f32_e32 v25, v25, v62
	v_mul_f32_e32 v27, v27, v62
	v_mul_f32_e32 v28, v28, v62
	v_mul_f32_e32 v29, v29, v62
	v_mul_f32_e32 v30, v30, v62
	v_mul_f32_e32 v31, v31, v62
	v_mul_f32_e32 v32, v32, v62
	v_mul_f32_e32 v33, v33, v62
	v_mul_f32_e32 v34, v34, v62
	v_mul_f32_e32 v35, v62, v35
	global_load_dword v62, v89, s[4:5] offset:384
	s_lshl_b32 s4, s72, 1
	s_add_u32 s0, s0, s4
	s_addc_u32 s1, s1, 0
	s_add_i32 s78, s78, s34
	s_add_i32 s76, s76, s34
	s_cmpk_lt_i32 s78, 0x400
	s_waitcnt vmcnt(0)
	v_mul_f32_e32 v18, v0, v62
	v_mul_f32_e32 v0, v3, v26
	v_mul_f32_e32 v26, v0, v62
	v_mul_f32_e32 v0, v4, v37
	v_mul_f32_e32 v37, v0, v62
	v_mul_f32_e32 v0, v5, v53
	v_mul_f32_e32 v53, v0, v62
	v_mul_f32_e32 v0, v6, v70
	v_mul_f32_e32 v89, v0, v62
	v_mul_f32_e32 v0, v7, v71
	v_mul_f32_e32 v90, v0, v62
	v_mul_f32_e32 v0, v8, v76
	v_mul_f32_e32 v76, v0, v62
	v_mul_f32_e32 v0, v9, v82
	v_mul_f32_e32 v82, v0, v62
	v_mul_f32_e32 v0, v10, v84
	v_mul_f32_e32 v84, v0, v62
	v_mul_f32_e32 v0, v11, v86
	v_mul_f32_e32 v86, v0, v62
	v_mul_f32_e32 v0, v12, v87
	v_mul_f32_e32 v87, v0, v62
	v_mul_f32_e32 v0, v13, v85
	v_mul_f32_e32 v85, v0, v62
	v_mul_f32_e32 v0, v14, v83
	v_mul_f32_e32 v83, v0, v62
	v_mul_f32_e32 v0, v15, v81
	v_mul_f32_e32 v81, v0, v62
	v_mul_f32_e32 v0, v16, v74
	v_mul_f32_e32 v91, v0, v62
	v_mul_f32_e32 v0, v17, v72
	v_mul_f32_e32 v92, v62, v0
	v_mov_b32_e32 v0, v228
	s_nop 0
	v_ashrrev_i32_e32 v4, 1, v0
	v_and_b32_e32 v3, 31, v0
	v_and_b32_e32 v4, 0xffffffe0, v4
	v_lshrrev_b32_e32 v0, 3, v0
	v_and_or_b32 v4, v0, 4, v4
	v_lshlrev_b32_e32 v0, 1, v3
	v_ashrrev_i32_e32 v5, 31, v4
	v_or_b32_e32 v10, 1, v4
	v_lshl_add_u64 v[6:7], s[0:1], 0, v[0:1]
	v_lshlrev_b64 v[8:9], 11, v[4:5]
	v_ashrrev_i32_e32 v11, 31, v10
	v_or_b32_e32 v12, 2, v4
	v_cvt_pk_bf16_f32 v0, v88, s0
	v_lshl_add_u64 v[8:9], v[6:7], 0, v[8:9]
	v_lshlrev_b64 v[10:11], 11, v[10:11]
	v_ashrrev_i32_e32 v13, 31, v12
	v_or_b32_e32 v14, 3, v4
	global_store_short v[8:9], v0, off
	v_cvt_pk_bf16_f32 v0, v80, s0
	v_lshl_add_u64 v[10:11], v[6:7], 0, v[10:11]
	v_lshlrev_b64 v[12:13], 11, v[12:13]
	v_ashrrev_i32_e32 v15, 31, v14
	v_or_b32_e32 v16, 8, v4
	global_store_short v[10:11], v0, off
	v_cvt_pk_bf16_f32 v0, v79, s0
	v_lshl_add_u64 v[12:13], v[6:7], 0, v[12:13]
	v_lshlrev_b64 v[14:15], 11, v[14:15]
	v_ashrrev_i32_e32 v17, 31, v16
	v_or_b32_e32 v62, 9, v4
	global_store_short v[12:13], v0, off
	v_cvt_pk_bf16_f32 v0, v78, s0
	v_lshl_add_u64 v[14:15], v[6:7], 0, v[14:15]
	v_lshlrev_b64 v[16:17], 11, v[16:17]
	v_ashrrev_i32_e32 v63, 31, v62
	v_or_b32_e32 v64, 10, v4
	global_store_short v[14:15], v0, off
	v_cvt_pk_bf16_f32 v0, v77, s0
	v_lshl_add_u64 v[16:17], v[6:7], 0, v[16:17]
	v_lshlrev_b64 v[62:63], 11, v[62:63]
	v_ashrrev_i32_e32 v65, 31, v64
	v_or_b32_e32 v66, 11, v4
	global_store_short v[16:17], v0, off
	v_cvt_pk_bf16_f32 v0, v75, s0
	v_lshl_add_u64 v[62:63], v[6:7], 0, v[62:63]
	v_lshlrev_b64 v[64:65], 11, v[64:65]
	v_ashrrev_i32_e32 v67, 31, v66
	global_store_short v[62:63], v0, off
	v_cvt_pk_bf16_f32 v0, v73, s0
	v_lshl_add_u64 v[64:65], v[6:7], 0, v[64:65]
	v_lshlrev_b64 v[66:67], 11, v[66:67]
	v_or_b32_e32 v68, 16, v4
	global_store_short v[64:65], v0, off
	v_cvt_pk_bf16_f32 v0, v61, s0
	v_lshl_add_u64 v[66:67], v[6:7], 0, v[66:67]
	v_ashrrev_i32_e32 v69, 31, v68
	global_store_short v[66:67], v0, off
	v_cvt_pk_bf16_f32 v0, v60, s0
	v_lshlrev_b64 v[60:61], 11, v[68:69]
	v_or_b32_e32 v68, 17, v4
	v_ashrrev_i32_e32 v69, 31, v68
	v_lshl_add_u64 v[60:61], v[6:7], 0, v[60:61]
	v_lshlrev_b64 v[68:69], 11, v[68:69]
	v_or_b32_e32 v70, 18, v4
	global_store_short v[60:61], v0, off
	v_cvt_pk_bf16_f32 v0, v59, s0
	v_lshl_add_u64 v[68:69], v[6:7], 0, v[68:69]
	v_ashrrev_i32_e32 v71, 31, v70
	global_store_short v[68:69], v0, off
	v_cvt_pk_bf16_f32 v0, v58, s0
	v_lshlrev_b64 v[58:59], 11, v[70:71]
	v_or_b32_e32 v70, 19, v4
	v_ashrrev_i32_e32 v71, 31, v70
	v_lshl_add_u64 v[58:59], v[6:7], 0, v[58:59]
	v_lshlrev_b64 v[70:71], 11, v[70:71]
	v_or_b32_e32 v72, 24, v4
	global_store_short v[58:59], v0, off
	v_cvt_pk_bf16_f32 v0, v57, s0
; __device__ __forceinline__ unsigned cvtpk(float lo, float hi) { f32x2_t v = {lo, hi}; bf16x2_t b = __builtin_convertvector(v, bf16x2_t); return __builtin_bit_cast(unsigned, b); }
; __device__ __forceinline__ int crowc(int r) { return (r & 3) + 8 * (r >> 2); }
; template <int DV>
; __device__ __forceinline__ void attn_store(const f32x16 (&o)[DV / 32], bf16_t* Op, int ldo) {
;     int tid_o = threadIdx.x; asm volatile("" : "+v"(tid_o));
;     const int lane = tid_o & 63, wid = tid_o >> 6, r32 = lane & 31, hi = lane >> 5;
; #pragma unroll
;     for (int dt = 0; dt < DV / 32; ++dt)
; #pragma unroll
;         for (int r = 0; r < 16; ++r) { const int row = 32 * wid + crowc(r) + 4 * hi; Op[(size_t)row * ldo + dt * 32 + r32] = (bf16_t)(cvtpk(o[dt][r], 0.f) & 0xffffu); }
; }
	v_lshl_add_u64 v[70:71], v[6:7], 0, v[70:71]
	v_ashrrev_i32_e32 v73, 31, v72
	global_store_short v[70:71], v0, off
	v_cvt_pk_bf16_f32 v0, v56, s0
	v_lshlrev_b64 v[56:57], 11, v[72:73]
	v_or_b32_e32 v72, 25, v4
	v_ashrrev_i32_e32 v73, 31, v72
	v_lshl_add_u64 v[56:57], v[6:7], 0, v[56:57]
	v_lshlrev_b64 v[72:73], 11, v[72:73]
	v_or_b32_e32 v74, 26, v4
	global_store_short v[56:57], v0, off
	v_cvt_pk_bf16_f32 v0, v55, s0
	v_lshl_add_u64 v[72:73], v[6:7], 0, v[72:73]
	v_ashrrev_i32_e32 v75, 31, v74
	global_store_short v[72:73], v0, off
	v_cvt_pk_bf16_f32 v0, v54, s0
	v_lshlrev_b64 v[54:55], 11, v[74:75]
	v_or_b32_e32 v4, 27, v4
	v_lshl_add_u64 v[54:55], v[6:7], 0, v[54:55]
	v_ashrrev_i32_e32 v5, 31, v4
	global_store_short v[54:55], v0, off
	v_cvt_pk_bf16_f32 v0, v2, s0
	v_lshlrev_b64 v[2:3], 11, v[4:5]
	v_lshl_add_u64 v[2:3], v[6:7], 0, v[2:3]
	global_store_short v[2:3], v0, off
	v_cvt_pk_bf16_f32 v0, v36, s0
	global_store_short v[8:9], v0, off offset:64
	v_cvt_pk_bf16_f32 v0, v38, s0
	global_store_short v[10:11], v0, off offset:64
	v_cvt_pk_bf16_f32 v0, v39, s0
	global_store_short v[12:13], v0, off offset:64
	v_cvt_pk_bf16_f32 v0, v40, s0
	global_store_short v[14:15], v0, off offset:64
	v_cvt_pk_bf16_f32 v0, v41, s0
	global_store_short v[16:17], v0, off offset:64
	v_cvt_pk_bf16_f32 v0, v42, s0
	global_store_short v[62:63], v0, off offset:64
	v_cvt_pk_bf16_f32 v0, v43, s0
	global_store_short v[64:65], v0, off offset:64
	v_cvt_pk_bf16_f32 v0, v44, s0
	global_store_short v[66:67], v0, off offset:64
	v_cvt_pk_bf16_f32 v0, v45, s0
	global_store_short v[60:61], v0, off offset:64
	v_cvt_pk_bf16_f32 v0, v46, s0
	global_store_short v[68:69], v0, off offset:64
	v_cvt_pk_bf16_f32 v0, v47, s0
	global_store_short v[58:59], v0, off offset:64
	v_cvt_pk_bf16_f32 v0, v48, s0
	global_store_short v[70:71], v0, off offset:64
	v_cvt_pk_bf16_f32 v0, v49, s0
	global_store_short v[56:57], v0, off offset:64
	v_cvt_pk_bf16_f32 v0, v50, s0
	global_store_short v[72:73], v0, off offset:64
	v_cvt_pk_bf16_f32 v0, v51, s0
	global_store_short v[54:55], v0, off offset:64
	v_cvt_pk_bf16_f32 v0, v52, s0
	global_store_short v[2:3], v0, off offset:64
	v_cvt_pk_bf16_f32 v0, v19, s0
	global_store_short v[8:9], v0, off offset:128
	v_cvt_pk_bf16_f32 v0, v20, s0
	global_store_short v[10:11], v0, off offset:128
	v_cvt_pk_bf16_f32 v0, v21, s0
	global_store_short v[12:13], v0, off offset:128
	v_cvt_pk_bf16_f32 v0, v22, s0
	global_store_short v[14:15], v0, off offset:128
	v_cvt_pk_bf16_f32 v0, v23, s0
	global_store_short v[16:17], v0, off offset:128
	v_cvt_pk_bf16_f32 v0, v24, s0
	global_store_short v[62:63], v0, off offset:128
	v_cvt_pk_bf16_f32 v0, v25, s0
	global_store_short v[64:65], v0, off offset:128
	v_cvt_pk_bf16_f32 v0, v27, s0
	global_store_short v[66:67], v0, off offset:128
	v_cvt_pk_bf16_f32 v0, v28, s0
	global_store_short v[60:61], v0, off offset:128
	v_cvt_pk_bf16_f32 v0, v29, s0
	global_store_short v[68:69], v0, off offset:128
	v_cvt_pk_bf16_f32 v0, v30, s0
	global_store_short v[58:59], v0, off offset:128
	v_cvt_pk_bf16_f32 v0, v31, s0
	global_store_short v[70:71], v0, off offset:128
	v_cvt_pk_bf16_f32 v0, v32, s0
	global_store_short v[56:57], v0, off offset:128
	v_cvt_pk_bf16_f32 v0, v33, s0
	global_store_short v[72:73], v0, off offset:128
	v_cvt_pk_bf16_f32 v0, v34, s0
	global_store_short v[54:55], v0, off offset:128
	v_cvt_pk_bf16_f32 v0, v35, s0
	global_store_short v[2:3], v0, off offset:128
	v_cvt_pk_bf16_f32 v0, v18, s0
	global_store_short v[8:9], v0, off offset:192
	v_cvt_pk_bf16_f32 v0, v26, s0
	global_store_short v[10:11], v0, off offset:192
	v_cvt_pk_bf16_f32 v0, v37, s0
	global_store_short v[12:13], v0, off offset:192
	v_cvt_pk_bf16_f32 v0, v53, s0
	global_store_short v[14:15], v0, off offset:192
	v_cvt_pk_bf16_f32 v0, v89, s0
	global_store_short v[16:17], v0, off offset:192
	v_cvt_pk_bf16_f32 v0, v90, s0
	global_store_short v[62:63], v0, off offset:192
	v_cvt_pk_bf16_f32 v0, v76, s0
	global_store_short v[64:65], v0, off offset:192
	v_cvt_pk_bf16_f32 v0, v82, s0
	global_store_short v[66:67], v0, off offset:192
	v_cvt_pk_bf16_f32 v0, v84, s0
	global_store_short v[60:61], v0, off offset:192
	v_cvt_pk_bf16_f32 v0, v86, s0
	global_store_short v[68:69], v0, off offset:192
	v_cvt_pk_bf16_f32 v0, v87, s0
	global_store_short v[58:59], v0, off offset:192
	v_cvt_pk_bf16_f32 v0, v85, s0
	global_store_short v[70:71], v0, off offset:192
	v_cvt_pk_bf16_f32 v0, v83, s0
	global_store_short v[56:57], v0, off offset:192
	v_cvt_pk_bf16_f32 v0, v81, s0
	global_store_short v[72:73], v0, off offset:192
	v_cvt_pk_bf16_f32 v0, v91, s0
	global_store_short v[54:55], v0, off offset:192
	v_cvt_pk_bf16_f32 v0, v92, s0
	global_store_short v[2:3], v0, off offset:192
	s_cbranch_scc0 .LBB0_863
